# static s_setprio 1 for waves 4-7 across the latent attention tile loop (skews the two co-resident waves)
# baseline (speedup 1.0000x reference)
.LBB0_206:
	s_andn2_b64 vcc, exec, s[0:1]
	s_cbranch_vccnz .LBB0_149
	v_mov_b32_e32 v20, v224
	s_ashr_i32 s2, s41, 4
	s_lshl_b32 s1, s41, 7
	v_readfirstlane_b32 s31, v20
	s_bfe_u32 s58, s31, 0x20006
	s_lshl_b32 s0, s2, 11
	s_and_b32 s1, s1, 0x780
	s_or_b32 s0, s0, s1
	s_lshl_b32 s1, s58, 5
	v_and_b32_e32 v21, 31, v20
	s_or_b32 s0, s1, s0
	v_or_b32_e32 v160, s0, v21
	s_ashr_i32 s59, s31, 8
	v_ashrrev_i32_e32 v161, 31, v160
	v_lshlrev_b64 v[0:1], 11, v[160:161]
	s_lshl_b32 s0, s59, 6
	v_bfe_u32 v163, v20, 5, 1
	v_lshl_add_u64 v[0:1], s[34:35], 0, v[0:1]
	s_ashr_i32 s1, s0, 31
	v_lshl_add_u64 v[0:1], s[0:1], 1, v[0:1]
	v_lshlrev_b32_e32 v192, 4, v163
	v_lshl_add_u64 v[0:1], v[0:1], 0, v[192:193]
	global_load_dwordx4 v[112:115], v[0:1], off
	global_load_dwordx4 v[116:119], v[0:1], off offset:32
	global_load_dwordx4 v[120:123], v[0:1], off offset:64
	s_lshl_b32 s0, s2, 3
	global_load_dwordx4 v[124:127], v[0:1], off offset:96
	s_or_b32 s0, s0, s54
	s_lshl_b32 s1, s0, 1
	s_mul_i32 s4, s0, 0x90000
	s_mul_hi_i32 s1, s1, 0x48000
	s_add_u32 s2, s56, s4
	s_addc_u32 s3, s57, s1
	s_mul_hi_i32 s0, s0, 0x90000
	s_add_u32 s48, s44, s4
	s_addc_u32 s49, s45, s0
	s_add_u32 s62, s2, 0x48000
	s_addc_u32 s63, s3, 0
	s_add_u32 s4, s48, 0x48000
	s_addc_u32 s5, s49, 0
	s_and_b32 s0, s41, -16
	s_add_i32 s0, s0, s75
	s_add_i32 s0, s0, s59
	s_ashr_i32 s1, s0, 31
	v_ashrrev_i32_e32 v2, 3, v20
	v_and_b32_e32 v3, 7, v20
	s_lshl_b64 s[0:1], s[0:1], 2
	v_readlane_b32 s9, v252, 46
	v_lshlrev_b32_e32 v165, 7, v2
	v_lshlrev_b32_e32 v3, 4, v3
	s_add_u32 s0, s9, s0
	v_readlane_b32 s9, v252, 47
	v_or_b32_e32 v26, v165, v3
	s_addc_u32 s1, s9, s1
	global_load_dwordx4 v[128:131], v26, s[2:3]
	global_load_dwordx4 v[132:135], v26, s[62:63]
	global_load_dword v27, v193, s[0:1]
	v_mul_lo_u32 v2, v2, s7
	v_or_b32_e32 v167, v2, v3
	v_lshrrev_b32_e32 v22, 4, v20
	v_and_b32_e32 v24, 6, v20
	v_bfe_u32 v23, v20, 4, 3
	v_bitop3_b32 v25, v22, v20, 7 bitop3:0x28
	v_lshl_or_b32 v170, v25, 4, v165
	v_lshlrev_b32_e32 v21, 7, v21
	v_mov_b32_e32 v168, 0
	v_mov_b32_e32 v148, 0
	v_and_b32_e32 v166, 63, v20
	s_mov_b32 s64, 0
	v_add_u32_e32 v174, 0, v21
	v_add_u32_e32 v178, 0x4000, v26
	s_mov_b32 s41, 0
	v_mov_b32_e32 v149, v148
	v_mov_b32_e32 v150, v148
	v_mov_b32_e32 v151, v148
	v_mov_b32_e32 v144, v148
	v_mov_b32_e32 v145, v148
	v_mov_b32_e32 v146, v148
	v_mov_b32_e32 v147, v148
	v_mov_b32_e32 v140, v148
	v_mov_b32_e32 v141, v148
	v_mov_b32_e32 v142, v148
	v_mov_b32_e32 v143, v148
	v_mov_b32_e32 v136, v148
	v_mov_b32_e32 v137, v148
	v_mov_b32_e32 v138, v148
	v_mov_b32_e32 v139, v148
	v_mov_b32_e32 v48, 0
	v_mov_b32_e32 v49, v168
	v_mov_b32_e32 v50, v168
	v_mov_b32_e32 v51, v168
	v_mov_b32_e32 v52, v168
	v_mov_b32_e32 v53, v168
	v_mov_b32_e32 v54, v168
	v_mov_b32_e32 v55, v168
	v_mov_b32_e32 v56, v168
	v_mov_b32_e32 v57, v168
	v_mov_b32_e32 v58, v168
	v_mov_b32_e32 v59, v168
	v_mov_b32_e32 v60, v168
	v_mov_b32_e32 v61, v168
	v_mov_b32_e32 v62, v168
	v_mov_b32_e32 v63, v168
	s_waitcnt vmcnt(0)
	v_and_b32_e32 v1, 0xffff0000, v112
	v_and_b32_e32 v3, 0xffff0000, v113
	v_lshlrev_b32_e32 v0, 16, v112
	v_lshlrev_b32_e32 v2, 16, v113
	v_and_b32_e32 v5, 0xffff0000, v114
	v_mul_f32_e32 v1, v1, v1
	v_mul_f32_e32 v3, v3, v3
	v_lshlrev_b32_e32 v4, 16, v114
	v_and_b32_e32 v7, 0xffff0000, v115
	v_mul_f32_e32 v5, v5, v5
	v_fmac_f32_e32 v1, v0, v0
	v_fmac_f32_e32 v3, v2, v2
	v_lshlrev_b32_e32 v6, 16, v115
	v_and_b32_e32 v9, 0xffff0000, v116
	v_mul_f32_e32 v7, v7, v7
	v_fmac_f32_e32 v5, v4, v4
	v_add_f32_e32 v0, v1, v3
	v_lshlrev_b32_e32 v8, 16, v116
	v_and_b32_e32 v11, 0xffff0000, v117
	v_mul_f32_e32 v9, v9, v9
	v_fmac_f32_e32 v7, v6, v6
	v_add_f32_e32 v0, v5, v0
	v_lshlrev_b32_e32 v10, 16, v117
	v_and_b32_e32 v13, 0xffff0000, v118
	v_mul_f32_e32 v11, v11, v11
	v_fmac_f32_e32 v9, v8, v8
	v_add_f32_e32 v0, v7, v0
	v_lshlrev_b32_e32 v12, 16, v118
	v_and_b32_e32 v15, 0xffff0000, v119
	v_mul_f32_e32 v13, v13, v13
	v_fmac_f32_e32 v11, v10, v10
	v_add_f32_e32 v0, v9, v0
	v_lshlrev_b32_e32 v14, 16, v119
	v_mul_f32_e32 v15, v15, v15
	v_fmac_f32_e32 v13, v12, v12
	v_add_f32_e32 v0, v11, v0
	v_fmac_f32_e32 v15, v14, v14
	v_add_f32_e32 v0, v13, v0
	v_add_f32_e32 v17, v15, v0
	global_load_dwordx4 v[0:3], v167, s[48:49]
	global_load_dwordx4 v[4:7], v167, s[4:5]
	v_add_u32_e32 v12, 0x2000, v26
	global_load_dwordx4 v[8:11], v12, s[2:3]
	s_nop 0
	global_load_dwordx4 v[12:15], v12, s[62:63]
	v_and_b32_e32 v18, 0xffff0000, v120
	v_lshlrev_b32_e32 v16, 16, v120
	v_mul_f32_e32 v18, v18, v18
	v_fmac_f32_e32 v18, v16, v16
	v_add_f32_e32 v16, v18, v17
	v_and_b32_e32 v18, 0xffff0000, v121
	v_lshlrev_b32_e32 v17, 16, v121
	v_mul_f32_e32 v18, v18, v18
	v_fmac_f32_e32 v18, v17, v17
	v_add_f32_e32 v28, v18, v16
	v_and_b32_e32 v19, 0xffff0000, v123
	v_and_b32_e32 v18, 0xffff0000, v122
	v_lshlrev_b32_e32 v17, 16, v123
	v_lshlrev_b32_e32 v16, 16, v122
	v_pk_mul_f32 v[18:19], v[18:19], v[18:19]
	v_mov_b32_e32 v32, 0
	v_pk_fma_f32 v[16:17], v[16:17], v[16:17], v[18:19]
	v_and_b32_e32 v19, 0xffff0000, v125
	v_add_f32_e32 v16, v16, v28
	v_and_b32_e32 v18, 0xffff0000, v124
	v_add_f32_e32 v28, v17, v16
	v_lshlrev_b32_e32 v17, 16, v125
	v_lshlrev_b32_e32 v16, 16, v124
	v_pk_mul_f32 v[18:19], v[18:19], v[18:19]
	v_mov_b32_e32 v33, v168
	v_pk_fma_f32 v[16:17], v[16:17], v[16:17], v[18:19]
	v_and_b32_e32 v19, 0xffff0000, v127
	v_add_f32_e32 v16, v16, v28
	v_and_b32_e32 v18, 0xffff0000, v126
	v_add_f32_e32 v28, v17, v16
	v_lshlrev_b32_e32 v17, 16, v127
	v_lshlrev_b32_e32 v16, 16, v126
	v_pk_mul_f32 v[18:19], v[18:19], v[18:19]
	v_mov_b32_e32 v34, v168
	v_pk_fma_f32 v[16:17], v[16:17], v[16:17], v[18:19]
	v_and_b32_e32 v18, 64, v229
	v_add_f32_e32 v16, v16, v28
	v_add_f32_e32 v16, v17, v16
	v_xor_b32_e32 v17, 32, v229
	v_add_u32_e32 v18, 64, v18
	v_cmp_lt_i32_e32 vcc, v17, v18
	v_lshlrev_b32_e32 v19, 3, v20
	v_bitop3_b32 v18, v22, v24, 7 bitop3:0x6c
	v_cndmask_b32_e32 v17, v229, v17, vcc
	v_lshlrev_b32_e32 v164, 2, v17
	ds_bpermute_b32 v17, v164, v16
	v_and_b32_e32 v19, 8, v19
	v_bitop3_b32 v22, v24, v23, 1 bitop3:0x36
	v_lshl_or_b32 v172, v18, 4, v19
	v_lshl_or_b32 v169, v22, 4, v19
	s_waitcnt lgkmcnt(0)
	v_add_f32_e32 v16, v16, v17
	v_mul_f32_e32 v16, v27, v16
	v_mul_f32_e32 v17, 0x4f800000, v16
	v_cmp_gt_f32_e32 vcc, s92, v16
	v_mov_b32_e32 v35, v168
	v_mov_b32_e32 v36, v168
	v_cndmask_b32_e32 v16, v16, v17, vcc
	v_sqrt_f32_e32 v17, v16
	v_mov_b32_e32 v37, v168
	v_mov_b32_e32 v38, v168
	v_mov_b32_e32 v39, v168
	v_add_u32_e32 v18, -1, v17
	v_fma_f32 v19, -v18, v17, v16
	v_cmp_ge_f32_e64 s[0:1], 0, v19
	v_add_u32_e32 v19, 1, v17
	v_mov_b32_e32 v40, v168
	v_cndmask_b32_e64 v18, v17, v18, s[0:1]
	v_fma_f32 v17, -v19, v17, v16
	v_cmp_lt_f32_e64 s[0:1], 0, v17
	v_mov_b32_e32 v41, v168
	v_mov_b32_e32 v42, v168
	v_cndmask_b32_e64 v17, v18, v19, s[0:1]
	v_mul_f32_e32 v18, 0x37800000, v17
	v_cndmask_b32_e32 v17, v17, v18, vcc
	v_cmp_class_f32_e32 vcc, v16, v228
	v_add_u32_e32 v18, 0, v165
	v_add_u32_e32 v19, v18, v172
	v_cndmask_b32_e32 v16, v17, v16, vcc
	v_fmamk_f32 v16, v16, 0x3f828f5c, v227
	v_add_u32_e32 v17, 0, v170
	v_xor_b32_e32 v64, 0x80000000, v16
	v_lshrrev_b32_e32 v16, 1, v20
	s_lshl_b32 s0, s59, 13
	ds_write_b128 v17, v[128:131]
	ds_write_b128 v17, v[132:135] offset:8192
	s_waitcnt vmcnt(3)
	ds_write_b64 v19, v[0:1] offset:49152
	v_add_u32_e32 v0, v18, v169
	s_waitcnt vmcnt(2)
	ds_write_b64 v19, v[4:5] offset:57344
	ds_write2st64_b64 v0, v[2:3], v[6:7] offset0:96 offset1:112
	s_waitcnt vmcnt(1)
	ds_write_b128 v17, v[8:11] offset:16384
	s_waitcnt vmcnt(0)
	ds_write_b128 v17, v[12:15] offset:24576
	s_add_i32 s0, s0, 0
	v_bitop3_b32 v0, v163, v16, 7 bitop3:0x78
	v_add_u32_e32 v177, s0, v21
	v_lshlrev_b32_e32 v176, 4, v0
	v_add_u32_e32 v4, v177, v176
	s_waitcnt lgkmcnt(0)
	s_barrier
	ds_read_b128 v[0:3], v4
	ds_read_b128 v[4:7], v4 offset:4096
	v_mov_b32_e32 v65, v64
	v_mov_b32_e32 v66, v64
	v_mov_b32_e32 v67, v64
	v_mov_b32_e32 v68, v64
	v_mov_b32_e32 v69, v64
	v_mov_b32_e32 v70, v64
	v_mov_b32_e32 v71, v64
	v_mov_b32_e32 v72, v64
	v_mov_b32_e32 v73, v64
	v_mov_b32_e32 v74, v64
	v_mov_b32_e32 v75, v64
	v_mov_b32_e32 v76, v64
	v_mov_b32_e32 v77, v64
	v_mov_b32_e32 v78, v64
	v_mov_b32_e32 v79, v64
	v_bfe_u32 v16, v20, 1, 3
	v_mov_b32_e32 v43, v168
	s_waitcnt lgkmcnt(1)
	v_mfma_f32_32x32x16_bf16 v[96:111], v[0:3], v[112:115], v[64:79]
	v_bitop3_b32 v0, v163, v16, 2 bitop3:0x36
	v_lshlrev_b32_e32 v175, 4, v0
	v_add_u32_e32 v8, v177, v175
	ds_read_b128 v[0:3], v8
	ds_read_b128 v[8:11], v8 offset:4096
	v_mov_b32_e32 v44, v168
	v_mov_b32_e32 v45, v168
	v_mov_b32_e32 v46, v168
	s_waitcnt lgkmcnt(2)
	v_mfma_f32_32x32x16_bf16 v[80:95], v[4:7], v[112:115], v[64:79]
	v_mov_b32_e32 v47, v168
	v_mov_b32_e32 v20, v168
	v_mov_b32_e32 v21, v168
	v_mov_b32_e32 v22, v168
	v_mov_b32_e32 v23, v168
	v_mov_b32_e32 v24, v168
	v_mov_b32_e32 v25, v168
	s_waitcnt lgkmcnt(1)
	v_mfma_f32_32x32x16_bf16 v[96:111], v[0:3], v[116:119], v[96:111]
	v_bitop3_b32 v0, v163, v16, 4 bitop3:0x36
	v_lshlrev_b32_e32 v173, 4, v0
	v_add_u32_e32 v12, v177, v173
	ds_read_b128 v[0:3], v12
	ds_read_b128 v[12:15], v12 offset:4096
	v_mov_b32_e32 v26, v168
	v_mov_b32_e32 v27, v168
	v_mov_b32_e32 v28, v168
	s_waitcnt lgkmcnt(2)
	v_mfma_f32_32x32x16_bf16 v[80:95], v[8:11], v[116:119], v[80:95]
	v_mov_b32_e32 v29, v168
	v_mov_b32_e32 v30, v168
	v_mov_b32_e32 v31, v168
	v_mov_b32_e32 v4, v168
	v_mov_b32_e32 v5, v168
	v_mov_b32_e32 v6, v168
	v_mov_b32_e32 v7, v168
	s_waitcnt lgkmcnt(1)
	v_mfma_f32_32x32x16_bf16 v[96:111], v[0:3], v[120:123], v[96:111]
	v_bitop3_b32 v0, v163, v16, 6 bitop3:0x36
	v_lshlrev_b32_e32 v171, 4, v0
	v_add_u32_e32 v16, v177, v171
	ds_read_b128 v[0:3], v16
	ds_read_b128 v[16:19], v16 offset:4096
	v_mov_b32_e32 v8, v168
	v_mov_b32_e32 v9, v168
	v_mov_b32_e32 v10, v168
	s_waitcnt lgkmcnt(2)
	v_mfma_f32_32x32x16_bf16 v[80:95], v[12:15], v[120:123], v[80:95]
	v_mov_b32_e32 v11, v168
	v_mov_b32_e32 v12, v168
	v_mov_b32_e32 v13, v168
	v_mov_b32_e32 v14, v168
	v_mov_b32_e32 v15, v168
	s_waitcnt lgkmcnt(1)
	v_mfma_f32_32x32x16_bf16 v[96:111], v[0:3], v[124:127], v[96:111]
	v_mov_b32_e32 v0, 0
	v_mov_b32_e32 v1, v168
	v_mov_b32_e32 v2, v168
	v_mov_b32_e32 v3, v168
	s_waitcnt lgkmcnt(0)
	v_mfma_f32_32x32x16_bf16 v[80:95], v[16:19], v[124:127], v[80:95]
	v_mov_b32_e32 v16, 0
	v_mov_b32_e32 v17, v168
	v_mov_b32_e32 v18, v168
	v_mov_b32_e32 v19, v168
	v_readfirstlane_b32 vcc_lo, v224
	s_lshr_b32 vcc_lo, vcc_lo, 8
	s_cmp_eq_u32 vcc_lo, 0
	s_cbranch_scc1 .Lattn_prio_skip
	s_setprio 1
.Lattn_prio_skip:
.LBB0_208:
	global_load_dwordx4 v[152:155], v167, s[48:49]
	global_load_dwordx4 v[156:159], v167, s[4:5]
	s_cmp_lt_u32 s41, 34
	s_cselect_b64 s[0:1], -1, 0
	s_cmp_gt_u32 s41, 33
	s_cbranch_scc1 .LBB0_210
	global_load_dwordx4 v[128:131], v178, s[2:3]
	global_load_dwordx4 v[132:135], v178, s[62:63]

.LBB0_214:
	s_setprio 0
	v_add_u32_e32 v68, v174, v176
	ds_read_b128 v[64:67], v68 offset:49152
	s_cmp_eq_u32 s59, 1
	s_waitcnt lgkmcnt(0)
	v_mfma_f32_32x32x16_bf16 v[48:63], v[64:67], v[148:151], v[48:63]
	ds_read_b128 v[64:67], v68 offset:53248
	s_waitcnt lgkmcnt(0)
	v_mfma_f32_32x32x16_bf16 v[32:47], v[64:67], v[148:151], v[32:47]
	ds_read_b128 v[64:67], v68 offset:57344
	s_waitcnt lgkmcnt(0)
	v_mfma_f32_32x32x16_bf16 v[16:31], v[64:67], v[148:151], v[16:31]
	ds_read_b128 v[64:67], v68 offset:61440
	v_add_u32_e32 v68, v174, v175
	s_waitcnt lgkmcnt(0)
	v_mfma_f32_32x32x16_bf16 v[0:15], v[64:67], v[148:151], v[0:15]
	ds_read_b128 v[64:67], v68 offset:49152
	s_waitcnt lgkmcnt(0)
	v_mfma_f32_32x32x16_bf16 v[48:63], v[64:67], v[144:147], v[48:63]
	ds_read_b128 v[64:67], v68 offset:53248
	s_waitcnt lgkmcnt(0)
	v_mfma_f32_32x32x16_bf16 v[32:47], v[64:67], v[144:147], v[32:47]
	ds_read_b128 v[64:67], v68 offset:57344
	s_waitcnt lgkmcnt(0)
	v_mfma_f32_32x32x16_bf16 v[16:31], v[64:67], v[144:147], v[16:31]
	ds_read_b128 v[64:67], v68 offset:61440
	v_add_u32_e32 v68, v174, v173
	s_waitcnt lgkmcnt(0)
	v_mfma_f32_32x32x16_bf16 v[0:15], v[64:67], v[144:147], v[0:15]
	ds_read_b128 v[64:67], v68 offset:49152
	s_waitcnt lgkmcnt(0)
	v_mfma_f32_32x32x16_bf16 v[48:63], v[64:67], v[140:143], v[48:63]
	ds_read_b128 v[64:67], v68 offset:53248
	s_waitcnt lgkmcnt(0)
	v_mfma_f32_32x32x16_bf16 v[32:47], v[64:67], v[140:143], v[32:47]
	ds_read_b128 v[64:67], v68 offset:57344
	s_waitcnt lgkmcnt(0)
	v_mfma_f32_32x32x16_bf16 v[16:31], v[64:67], v[140:143], v[16:31]
	ds_read_b128 v[64:67], v68 offset:61440
	v_add_u32_e32 v68, v174, v171
	s_waitcnt lgkmcnt(0)
	v_mfma_f32_32x32x16_bf16 v[0:15], v[64:67], v[140:143], v[0:15]
	ds_read_b128 v[64:67], v68 offset:49152
	s_waitcnt lgkmcnt(0)
	v_mfma_f32_32x32x16_bf16 v[48:63], v[64:67], v[136:139], v[48:63]
	ds_read_b128 v[64:67], v68 offset:53248
	s_waitcnt lgkmcnt(0)
	v_mfma_f32_32x32x16_bf16 v[32:47], v[64:67], v[136:139], v[32:47]
	ds_read_b128 v[64:67], v68 offset:57344
	s_waitcnt lgkmcnt(0)
	v_mfma_f32_32x32x16_bf16 v[16:31], v[64:67], v[136:139], v[16:31]
	ds_read_b128 v[64:67], v68 offset:61440
	s_waitcnt lgkmcnt(0)
	v_mfma_f32_32x32x16_bf16 v[0:15], v[64:67], v[136:139], v[0:15]
	ds_bpermute_b32 v64, v164, v168
	s_waitcnt lgkmcnt(0)
	v_add_f32_e32 v64, v168, v64
	v_div_scale_f32 v65, s[0:1], v64, v64, 1.0
	v_rcp_f32_e32 v66, v65
	s_nop 0
	v_fma_f32 v67, -v65, v66, 1.0
	v_fmac_f32_e32 v66, v67, v66
	v_div_scale_f32 v67, vcc, 1.0, v64, 1.0
	v_mul_f32_e32 v68, v67, v66
	v_fma_f32 v69, -v65, v68, v67
	v_fmac_f32_e32 v68, v69, v66
	v_fma_f32 v65, -v65, v68, v67
	v_div_fmas_f32 v65, v65, v66, v68
	v_div_fixup_f32 v64, v65, v64, 1.0
	s_cbranch_scc0 .LBB0_216
	s_lshl_b32 s0, s58, 14
	s_add_i32 s0, s0, 0
	v_lshl_add_u32 v66, v166, 2, s0
	v_mul_f32_e32 v65, v48, v64
	v_add_u32_e32 v66, 0x10000, v66
	v_mul_f32_e32 v67, v49, v64
	ds_write2st64_b32 v66, v65, v67 offset1:1
	v_mul_f32_e32 v65, v50, v64
	v_mul_f32_e32 v67, v51, v64
	ds_write2st64_b32 v66, v65, v67 offset0:2 offset1:3
	v_mul_f32_e32 v65, v52, v64
	v_mul_f32_e32 v67, v53, v64
	ds_write2st64_b32 v66, v65, v67 offset0:4 offset1:5
	v_mul_f32_e32 v65, v54, v64
	v_mul_f32_e32 v67, v55, v64
	ds_write2st64_b32 v66, v65, v67 offset0:6 offset1:7
	v_mul_f32_e32 v65, v56, v64
	v_mul_f32_e32 v67, v57, v64
	ds_write2st64_b32 v66, v65, v67 offset0:8 offset1:9
	v_mul_f32_e32 v65, v58, v64
	v_mul_f32_e32 v67, v59, v64
	ds_write2st64_b32 v66, v65, v67 offset0:10 offset1:11
	v_mul_f32_e32 v65, v60, v64
	v_mul_f32_e32 v67, v61, v64
	ds_write2st64_b32 v66, v65, v67 offset0:12 offset1:13
	v_mul_f32_e32 v65, v62, v64
	v_mul_f32_e32 v67, v63, v64
	ds_write2st64_b32 v66, v65, v67 offset0:14 offset1:15
	v_mul_f32_e32 v65, v32, v64
	v_mul_f32_e32 v67, v33, v64
	ds_write2st64_b32 v66, v65, v67 offset0:16 offset1:17
	v_mul_f32_e32 v65, v34, v64
	v_mul_f32_e32 v67, v35, v64
	ds_write2st64_b32 v66, v65, v67 offset0:18 offset1:19
	v_mul_f32_e32 v65, v36, v64
	v_mul_f32_e32 v67, v37, v64
	ds_write2st64_b32 v66, v65, v67 offset0:20 offset1:21
	v_mul_f32_e32 v65, v38, v64
	v_mul_f32_e32 v67, v39, v64
	ds_write2st64_b32 v66, v65, v67 offset0:22 offset1:23
	v_mul_f32_e32 v65, v40, v64
	v_mul_f32_e32 v67, v41, v64
	ds_write2st64_b32 v66, v65, v67 offset0:24 offset1:25
	v_mul_f32_e32 v65, v42, v64
	v_mul_f32_e32 v67, v43, v64
	ds_write2st64_b32 v66, v65, v67 offset0:26 offset1:27
	v_mul_f32_e32 v65, v44, v64
	v_mul_f32_e32 v67, v45, v64
	ds_write2st64_b32 v66, v65, v67 offset0:28 offset1:29
	v_mul_f32_e32 v65, v46, v64
	v_mul_f32_e32 v67, v47, v64
	ds_write2st64_b32 v66, v65, v67 offset0:30 offset1:31
	v_mul_f32_e32 v65, v16, v64
	v_mul_f32_e32 v67, v17, v64
	ds_write2st64_b32 v66, v65, v67 offset0:32 offset1:33
	v_mul_f32_e32 v65, v18, v64
	v_mul_f32_e32 v67, v19, v64
	ds_write2st64_b32 v66, v65, v67 offset0:34 offset1:35
	v_mul_f32_e32 v65, v20, v64
	v_mul_f32_e32 v67, v21, v64
	ds_write2st64_b32 v66, v65, v67 offset0:36 offset1:37
	v_mul_f32_e32 v65, v22, v64
	v_mul_f32_e32 v67, v23, v64
	ds_write2st64_b32 v66, v65, v67 offset0:38 offset1:39
	v_mul_f32_e32 v65, v24, v64
	v_mul_f32_e32 v67, v25, v64
	ds_write2st64_b32 v66, v65, v67 offset0:40 offset1:41
	v_mul_f32_e32 v65, v26, v64
	v_mul_f32_e32 v67, v27, v64
	ds_write2st64_b32 v66, v65, v67 offset0:42 offset1:43
	v_mul_f32_e32 v65, v28, v64
	v_mul_f32_e32 v67, v29, v64
	ds_write2st64_b32 v66, v65, v67 offset0:44 offset1:45
	v_mul_f32_e32 v65, v30, v64
	v_mul_f32_e32 v67, v31, v64
	ds_write2st64_b32 v66, v65, v67 offset0:46 offset1:47
	v_mul_f32_e32 v65, v0, v64
	v_mul_f32_e32 v67, v1, v64
	ds_write2st64_b32 v66, v65, v67 offset0:48 offset1:49
	v_mul_f32_e32 v65, v2, v64
	v_mul_f32_e32 v67, v3, v64
	ds_write2st64_b32 v66, v65, v67 offset0:50 offset1:51
	v_mul_f32_e32 v65, v4, v64
	v_mul_f32_e32 v67, v5, v64
	ds_write2st64_b32 v66, v65, v67 offset0:52 offset1:53
	v_mul_f32_e32 v65, v6, v64
	v_mul_f32_e32 v67, v7, v64
	ds_write2st64_b32 v66, v65, v67 offset0:54 offset1:55
	v_mul_f32_e32 v65, v8, v64
	v_mul_f32_e32 v67, v9, v64
	ds_write2st64_b32 v66, v65, v67 offset0:56 offset1:57
	v_mul_f32_e32 v65, v10, v64
	v_mul_f32_e32 v67, v11, v64
	ds_write2st64_b32 v66, v65, v67 offset0:58 offset1:59
	v_mul_f32_e32 v65, v12, v64
	v_mul_f32_e32 v67, v13, v64
	ds_write2st64_b32 v66, v65, v67 offset0:60 offset1:61
	v_mul_f32_e32 v65, v14, v64
	v_mul_f32_e32 v67, v15, v64
	ds_write2st64_b32 v66, v65, v67 offset0:62 offset1:63
